# gate queue: next tile's ticket fetched when a tile starts (atomic round trip hidden under the first DMA fetch)
# baseline (speedup 1.0000x reference)
; __device__ __forceinline__ void phase_scan(KP p, int l, unsigned char* smem) {
;     ...
;     unsigned* cnt = (unsigned*)(p->ws + OFF_CNT) + l * 64;
;     for (;;) {
;         __syncthreads();
;         if (tid_ == 0) s_q = (int)atomicAdd(cnt, 1u);
;         __syncthreads();
;         const int t = s_q;
.LBB0_165:
.LBB0_166:
	s_mov_b32 s2, 0
	v_writelane_b32 v234, s2, 8
	v_writelane_b32 v234, s2, 9
	v_readlane_b32 s12, v230, 25
	v_readlane_b32 s13, v230, 26
	s_mov_b32 s14, s12
	s_lshl_b32 s12, s12, 6
	s_ashr_i32 s13, s12, 31
	s_lshl_b64 s[12:13], s[12:13], 2
	s_add_u32 s2, s58, s12
	s_addc_u32 s11, s59, s13
	s_add_u32 s78, s2, 0x28cf3600
	s_addc_u32 s79, s11, 0
	s_add_u32 s11, s58, 0x2140000
	s_addc_u32 s39, s59, 0
	s_add_u32 s12, s58, 0x29df3a00
	s_addc_u32 s13, s59, 0
	s_lshl_b32 s97, s14, 5
	s_add_u32 s84, s58, 0x1bfe0000
	s_addc_u32 s85, s59, 0
	s_lshl_b32 s94, s14, 7
	v_cmp_eq_u32_e64 s[40:41], 0, v64
	v_writelane_b32 v230, s12, 34
	s_add_i32 s95, s94, -8
	s_lshl_b32 s96, s14, 3
	v_writelane_b32 v230, s13, 35
	s_branch .LBB0_170

; __device__ __forceinline__ void phase_scan(KP p, int l, unsigned char* smem) {
;     ...
;     for (;;) {
;         __syncthreads();
;         if (tid_ == 0) s_q = (int)atomicAdd(cnt, 1u);
;         __syncthreads();
.LBB0_170:
	s_barrier
	s_nop 1
	v_readlane_b32 s2, v234, 8
	s_nop 1
	v_mov_b32_e32 v236, s2
	s_and_saveexec_b64 s[14:15], s[40:41]
	s_cbranch_execz .LBB0_174
	v_readlane_b32 s18, v234, 9
	s_cmp_eq_u32 s18, 0
	s_cbranch_scc1 .Lq_nopf
	s_waitcnt vmcnt(0)
	ds_write_b32 v235, v253 offset:16
	s_branch .LBB0_174
.Lq_nopf:
	s_mov_b64 s[18:19], exec
	v_mbcnt_lo_u32_b32 v0, s18, 0
	v_mbcnt_hi_u32_b32 v0, s19, v0
	v_cmp_eq_u32_e32 vcc, 0, v0
	s_and_saveexec_b64 s[12:13], vcc
	s_cbranch_execz .LBB0_173
	s_bcnt1_i32_b64 s2, s[18:19]
	v_mov_b32_e32 v1, s2
	global_atomic_add v1, v236, v1, s[78:79] sc0

; __device__ __forceinline__ int tidx() { int t = threadIdx.x; asm volatile("" : "+v"(t)); return t; }
; __device__ __forceinline__ void gate_tile(int t, const bf16_t* xb, const bf16_t* Wg, bf16_t* G, bf16_t* sm) {
;     const int tid_ = tidx();
;     const int lane = tid_ & 63, wid = tid_ >> 6, wr = wid >> 1, wc = wid & 1, fr = lane & 15, fq = lane >> 4;
;     const int tm = t >> 5, tn = t & 31;
;     f32x4 acc[4][4]; zero_acc<4>(acc);
;     gemm_tile<4>(acc, xb + (size_t)tm * 128 * 1024, 1024, Wg + (size_t)tn * 128 * 1024, 1024, 1024, sm);
; __device__ __forceinline__ void phase_scan(KP p, int l, unsigned char* smem) {
;     ...
;         __syncthreads();
;         if (tid_ == 0) s_q = (int)atomicAdd(cnt, 1u);
;         __syncthreads();
;         const int t = s_q;
;         const int NGT = 136 * 32, NAT = 1152, NMV = 256;
;         if (t >= NGT + NAT + NMV) break;
;         if (t < NMV) misc_vblock(p, l, t, NMV);
;         else if (t < NMV + NAT) attn_block_task(p, l, t - NMV);
;         else gate_tile(t - NMV - NAT, (const bf16_t*)(p->ws + OFF_XB), (const bf16_t*)(p->ws + OFF_WG), (bf16_t*)(p->ws + OFF_G), (bf16_t*)smem);
.LBB0_174:
	s_or_b64 exec, exec, s[14:15]
	s_waitcnt lgkmcnt(0)
	s_barrier
	ds_read_b32 v0, v235 offset:16
	s_mov_b64 s[12:13], -1
	s_waitcnt lgkmcnt(0)
	v_readfirstlane_b32 s74, v0
	s_mov_b32 s14, 0
	v_writelane_b32 v234, s14, 9
	s_nop 1
	v_readlane_b32 s2, v234, 8
	s_cmp_lg_u32 s2, 0
	s_cbranch_scc1 .Lq_xcd
	s_cmpk_gt_i32 s74, 0xff
	s_cbranch_scc0 .LBB0_189
	s_cmpk_gt_u32 s74, 0x57f
	s_cbranch_scc0 .LBB0_180
	v_readlane_b32 s2, v231, 56
	s_and_b32 s2, s2, 7
	s_lshl_b32 s2, s2, 2
	s_add_i32 s2, s2, 4
	v_writelane_b32 v234, s2, 8
	s_branch .LBB0_170
.Lq_xcd:
	s_cmpk_lt_u32 s74, 0x220
	s_cbranch_scc0 .LBB0_169
	s_lshr_b32 s14, s2, 2
	s_add_i32 s14, s14, -1
	s_mul_i32 s15, s74, 0x1e2
	s_lshr_b32 s15, s15, 16
	s_mul_i32 s18, s15, 0x88
	s_sub_i32 s18, s74, s18
	s_lshr_b32 s19, s18, 3
	s_and_b32 s18, s18, 7
	s_mul_i32 s14, s14, 17
	s_add_i32 s14, s14, s19
	s_lshl_b32 s15, s15, 3
	s_add_i32 s15, s15, s18
	s_lshl_b32 s14, s14, 5
	s_add_i32 s74, s14, s15
	s_addk_i32 s74, 0x580
	s_and_saveexec_b64 s[14:15], s[40:41]
	s_cbranch_execz .Lq_pf_skip
	v_mov_b32_e32 v253, 1
	global_atomic_add v253, v236, v253, s[78:79] sc0
.Lq_pf_skip:
	s_or_b64 exec, exec, s[14:15]
	s_mov_b32 s14, 1
	v_writelane_b32 v234, s14, 9
	v_mov_b32_e32 v12, v192
	v_mov_b32_e32 v40, v192
	s_add_i32 s2, s74, 0xfffffa80
	v_ashrrev_i32_e32 v0, 31, v40
	s_waitcnt vmcnt(6)
	v_ashrrev_i32_e32 v30, 3, v40
	v_lshrrev_b32_e32 v0, 26, v0
	v_add_u32_e32 v0, v30, v0
	v_lshrrev_b32_e32 v1, 6, v0
	v_mul_i32_i24_e32 v1, 64, v1
	v_sub_u32_e32 v1, v30, v1
	v_lshrrev_b16_sdwa v2, v196, sext(v1) dst_sel:DWORD dst_unused:UNUSED_PAD src0_sel:DWORD src1_sel:BYTE_0
	v_and_b32_e32 v2, 3, v2
	v_add_u16_e32 v2, v1, v2
	v_ashrrev_i16_sdwa v3, v197, sext(v2) dst_sel:DWORD dst_unused:UNUSED_PAD src0_sel:DWORD src1_sel:BYTE_0
	v_and_b32_e32 v2, 0xfc, v2
	v_sub_u16_e32 v1, v1, v2
	v_and_b32_e32 v0, 0x7ffffc0, v0
	v_lshlrev_b32_sdwa v1, v198, sext(v1) dst_sel:DWORD dst_unused:UNUSED_PAD src0_sel:DWORD src1_sel:BYTE_0
	v_bfe_i32 v2, v3, 0, 16
	v_add3_u32 v41, v0, v2, v1
	v_add_u32_e32 v0, 32, v30
	v_ashrrev_i32_e32 v1, 31, v0
	v_lshrrev_b32_e32 v1, 26, v1
	v_add_u32_e32 v1, v0, v1
	v_lshrrev_b32_e32 v2, 6, v1
	v_mul_i32_i24_e32 v2, 64, v2
	v_sub_u32_e32 v0, v0, v2
	v_lshrrev_b16_sdwa v2, v196, sext(v0) dst_sel:DWORD dst_unused:UNUSED_PAD src0_sel:DWORD src1_sel:BYTE_0
	v_and_b32_e32 v2, 3, v2
	v_add_u16_e32 v2, v0, v2
	v_ashrrev_i16_sdwa v3, v197, sext(v2) dst_sel:DWORD dst_unused:UNUSED_PAD src0_sel:DWORD src1_sel:BYTE_0
	v_and_b32_e32 v2, 0xfc, v2
	v_sub_u16_e32 v0, v0, v2
	v_and_b32_e32 v1, 0x7ffffc0, v1
	v_lshlrev_b32_sdwa v0, v198, sext(v0) dst_sel:DWORD dst_unused:UNUSED_PAD src0_sel:DWORD src1_sel:BYTE_0
	v_bfe_i32 v2, v3, 0, 16
	v_add3_u32 v42, v1, v2, v0
	v_add_u32_e32 v0, 64, v30
	v_ashrrev_i32_e32 v1, 31, v0
	v_lshrrev_b32_e32 v1, 26, v1
	v_add_u32_e32 v1, v0, v1
	v_lshrrev_b32_e32 v2, 6, v1
	v_mul_i32_i24_e32 v2, 64, v2
	v_sub_u32_e32 v0, v0, v2
	v_lshrrev_b16_sdwa v2, v196, sext(v0) dst_sel:DWORD dst_unused:UNUSED_PAD src0_sel:DWORD src1_sel:BYTE_0
	v_and_b32_e32 v2, 3, v2
	v_add_u16_e32 v2, v0, v2
	v_ashrrev_i16_sdwa v3, v197, sext(v2) dst_sel:DWORD dst_unused:UNUSED_PAD src0_sel:DWORD src1_sel:BYTE_0
	v_and_b32_e32 v2, 0xfc, v2
	v_sub_u16_e32 v0, v0, v2
	v_and_b32_e32 v1, 0x7ffffc0, v1
	v_lshlrev_b32_sdwa v0, v198, sext(v0) dst_sel:DWORD dst_unused:UNUSED_PAD src0_sel:DWORD src1_sel:BYTE_0
	v_bfe_i32 v2, v3, 0, 16
	v_add3_u32 v43, v1, v2, v0
	v_add_u32_e32 v0, 0x60, v30
	v_ashrrev_i32_e32 v1, 31, v0
	v_lshrrev_b32_e32 v1, 26, v1
	v_add_u32_e32 v1, v0, v1
	v_lshrrev_b32_e32 v2, 6, v1
	v_mul_i32_i24_e32 v2, 64, v2
	v_sub_u32_e32 v0, v0, v2
	s_lshr_b32 s13, s2, 5
	v_lshrrev_b16_sdwa v2, v196, sext(v0) dst_sel:DWORD dst_unused:UNUSED_PAD src0_sel:DWORD src1_sel:BYTE_0
	s_lshl_b32 s86, s13, 17
	v_and_b32_e32 v2, 3, v2
	s_and_b32 s12, s74, 31
	s_lshl_b64 s[14:15], s[86:87], 1
	v_add_u16_e32 v2, v0, v2
	s_add_u32 s18, s80, s14
	v_ashrrev_i16_sdwa v3, v197, sext(v2) dst_sel:DWORD dst_unused:UNUSED_PAD src0_sel:DWORD src1_sel:BYTE_0
	v_and_b32_e32 v2, 0xfc, v2
	s_addc_u32 s19, s81, s15
	s_lshl_b32 s2, s12, 18
	v_sub_u16_e32 v0, v0, v2
	s_add_u32 s22, s11, s2
	v_and_b32_e32 v1, 0x7ffffc0, v1
	v_lshlrev_b32_sdwa v0, v198, sext(v0) dst_sel:DWORD dst_unused:UNUSED_PAD src0_sel:DWORD src1_sel:BYTE_0
	v_bfe_i32 v2, v3, 0, 16
	v_ashrrev_i32_e32 v31, 31, v30
	s_addc_u32 s23, s39, 0
	v_add3_u32 v44, v1, v2, v0
	v_lshlrev_b64 v[32:33], 11, v[30:31]
	v_lshlrev_b32_e32 v2, 4, v40
	v_lshl_add_u64 v[0:1], s[22:23], 0, v[32:33]
	v_and_b32_e32 v38, 0x70, v2
	v_mov_b32_e32 v39, v13
	v_lshl_add_u64 v[8:9], v[0:1], 0, v[38:39]
	v_add_co_u32_e32 v0, vcc, s7, v8
	v_mul_lo_u32 v46, v30, s89
	s_nop 0
	v_addc_co_u32_e32 v1, vcc, 0, v9, vcc
	v_add_co_u32_e32 v10, vcc, s37, v8
	v_mov_b32_e32 v250, v8
	v_mov_b32_e32 v251, v9
	s_nop 0
	v_addc_co_u32_e32 v11, vcc, 0, v9, vcc
	v_add_co_u32_e32 v14, vcc, s73, v8
	v_and_b32_e32 v30, 7, v40
	s_nop 0
	v_addc_co_u32_e32 v15, vcc, 0, v9, vcc
	s_nop 0
	v_lshl_add_u64 v[14:15], s[18:19], 0, v[32:33]
	v_lshl_add_u64 v[26:27], v[14:15], 0, v[38:39]
	v_add_co_u32_e32 v14, vcc, s7, v26
	s_add_u32 s14, s58, s14
	s_nop 0
	v_addc_co_u32_e32 v15, vcc, 0, v27, vcc
	v_add_co_u32_e32 v28, vcc, s37, v26
	v_mov_b32_e32 v248, v26
	v_mov_b32_e32 v249, v27
	s_nop 0
	v_addc_co_u32_e32 v29, vcc, 0, v27, vcc
	v_add_co_u32_e32 v34, vcc, s73, v26
	v_and_b32_e32 v31, 15, v40
	s_nop 0
	v_addc_co_u32_e32 v35, vcc, 0, v27, vcc
	s_nop 0
	v_lshrrev_b32_e32 v39, 1, v40
	v_lshl_or_b32 v32, v30, 4, v32
	s_addc_u32 s15, s59, s15
; __device__ __forceinline__ int tidx() { int t = threadIdx.x; asm volatile("" : "+v"(t)); return t; }
; template <int NT>
; __device__ __forceinline__ void gemm_tile(f32x4 (&acc)[4][NT], const bf16_t* A, int lda, const bf16_t* B, int ldb, int K, bf16_t* sm) {
;     const int tid_ = tidx();
;     bf16_t* sA = sm; bf16_t* sB = sm + 128 * LDT;
;     const int tid = tid_, lane = tid & 63, wid = tid >> 6, wr = wid >> 1, wc = wid & 1;
;     const int fr = lane & 15, fq = lane >> 4;
;     const int lrow = tid >> 3, lkc = tid & 7;
;     const bf16_t* ga = A + (size_t)lrow * lda + lkc * 8;
;     const bf16_t* gb = B + (size_t)lrow * ldb + lkc * 8;
;     int sbrow[NT];
; #pragma unroll
;     for (int i = 0; i < NT; ++i) { const int g = lrow + 32 * i, W_ = 16 * NT, rem = g % W_; sbrow[i] = (g / W_) * W_ + (rem % NT) * 16 + rem / NT; }
;     u32x4 ra0[4], rb0[NT];
; #pragma unroll
;     for (int i = 0; i < 4; ++i) ra0[i] = *(const u32x4*)(ga + (size_t)(32 * i) * lda);
; #pragma unroll
;     for (int i = 0; i < NT; ++i) rb0[i] = *(const u32x4*)(gb + (size_t)(32 * i) * ldb);
;     const int nk = K >> 6;
;     for (int kt = 0; kt < nk; ++kt) {
;         lds_barrier();
; #pragma unroll
;         for (int i = 0; i < 4; ++i) *(u32x4*)(sA + (lrow + 32 * i) * LDT + lkc * 8) = ra0[i];
; #pragma unroll
;         for (int i = 0; i < NT; ++i) *(u32x4*)(sB + sbrow[i] * LDT + lkc * 8) = rb0[i];
;         lds_barrier();
;         if (kt + 1 < nk) {
;             ga += 64; gb += 64;
; #pragma unroll
;             for (int i = 0; i < 4; ++i) ra0[i] = *(const u32x4*)(ga + (size_t)(32 * i) * lda);
; #pragma unroll
;             for (int i = 0; i < NT; ++i) rb0[i] = *(const u32x4*)(gb + (size_t)(32 * i) * ldb);
;         }
; template <int NT> __device__ __forceinline__ void zero_acc(f32x4 (&acc)[4][NT]) {
; #pragma unroll
;     for (int mt = 0; mt < 4; ++mt)
; #pragma unroll
;         for (int nt = 0; nt < NT; ++nt) acc[mt][nt] = (f32x4){0.f, 0.f, 0.f, 0.f};
; }
	v_and_or_b32 v31, v39, s3, v31
	v_and_b32_e32 v39, 0x4f, v40
	v_lshl_add_u64 v[98:99], s[14:15], 0, v[32:33]
	s_add_u32 s14, s58, s2
	v_and_b32_e32 v45, 48, v40
	v_mul_lo_u32 v31, v31, s89
	v_mul_u32_u24_e32 v39, 0xa0, v39
	v_mul_lo_u32 v41, v41, s89
	v_mul_lo_u32 v42, v42, s89
	v_mul_lo_u32 v43, v43, s89
	v_mul_lo_u32 v44, v44, s89
	s_addc_u32 s15, s59, 0
	v_mov_b32_e32 v30, 0
	v_lshl_add_u64 v[100:101], s[14:15], 0, v[32:33]
	s_mov_b64 s[14:15], 0
	v_add_u32_e32 v104, v38, v46
	v_add_u32_e32 v105, v38, v41
	v_add_u32_e32 v106, v38, v42
	v_add_u32_e32 v107, v38, v43
	v_add_u32_e32 v108, v38, v44
	v_add_u32_e32 v103, v45, v31
	v_add_u32_e32 v102, v45, v39
	v_mov_b32_e32 v31, v30
	v_mov_b32_e32 v32, v30
	v_mov_b32_e32 v33, v30
	v_mov_b32_e32 v38, v30
	v_mov_b32_e32 v39, v30
	v_mov_b32_e32 v40, v30
	v_mov_b32_e32 v41, v30
	v_mov_b32_e32 v42, v30
	v_mov_b32_e32 v43, v30
	v_mov_b32_e32 v44, v30
	v_mov_b32_e32 v45, v30
	v_mov_b32_e32 v46, v30
	v_mov_b32_e32 v47, v30
	v_mov_b32_e32 v48, v30
	v_mov_b32_e32 v49, v30
	v_mov_b32_e32 v50, v30
	v_mov_b32_e32 v51, v30
	v_mov_b32_e32 v52, v30
	v_mov_b32_e32 v53, v30
	v_mov_b32_e32 v54, v30
	v_mov_b32_e32 v55, v30
	v_mov_b32_e32 v56, v30
	v_mov_b32_e32 v57, v30
	v_mov_b32_e32 v58, v30
	v_mov_b32_e32 v59, v30
	v_mov_b32_e32 v60, v30
	v_mov_b32_e32 v61, v30
	v_mov_b32_e32 v62, v30
	v_mov_b32_e32 v63, v30
	v_mov_b32_e32 v64, v30
	v_mov_b32_e32 v65, v30
	v_mov_b32_e32 v66, v30
	v_mov_b32_e32 v67, v30
	v_mov_b32_e32 v68, v30
	v_mov_b32_e32 v69, v30
	v_mov_b32_e32 v70, v30
	v_mov_b32_e32 v71, v30
	v_mov_b32_e32 v72, v30
	v_mov_b32_e32 v73, v30
	v_mov_b32_e32 v74, v30
	v_mov_b32_e32 v75, v30
	v_mov_b32_e32 v76, v30
	v_mov_b32_e32 v77, v30
	v_mov_b32_e32 v78, v30
	v_mov_b32_e32 v79, v30
	v_mov_b32_e32 v80, v30
	v_mov_b32_e32 v81, v30
	v_mov_b32_e32 v82, v30
	v_mov_b32_e32 v83, v30
	v_mov_b32_e32 v84, v30
	v_mov_b32_e32 v85, v30
	v_mov_b32_e32 v86, v30
	v_mov_b32_e32 v87, v30
	v_mov_b32_e32 v88, v30
	v_mov_b32_e32 v89, v30
	v_mov_b32_e32 v90, v30
	v_mov_b32_e32 v91, v30
	v_mov_b32_e32 v92, v30
	v_mov_b32_e32 v93, v30
	v_mov_b32_e32 v94, v30
	v_mov_b32_e32 v95, v30
	v_mov_b32_e32 v96, v30
	v_mov_b32_e32 v97, v30
	v_writelane_b32 v234, s90, 0
	v_writelane_b32 v234, s91, 1
	v_writelane_b32 v234, s92, 2
	v_writelane_b32 v234, s93, 3
	v_writelane_b32 v234, s94, 4
	v_writelane_b32 v234, s95, 5
	v_bfe_u32 v160, v192, 3, 3
	v_and_b32_e32 v161, 7, v192
	v_xor_b32_e32 v161, v160, v161
	v_lshlrev_b32_e32 v161, 4, v161
	v_lshrrev_b32_e32 v162, 6, v192
	v_lshl_add_u32 v163, v162, 5, v160
	v_mul_u32_u24_e32 v163, 0x800, v163
	v_add_u32_e32 v236, v163, v161
	v_add_u32_e32 v237, 0x3c00, v236
	v_add_u32_e32 v238, 0x3c00, v237
	v_add_u32_e32 v239, 0x3c00, v238
	v_lshrrev_b32_e32 v163, 7, v192
	v_bfe_u32 v162, v192, 6, 1
	v_lshlrev_b32_e32 v163, 6, v163
	v_lshl_add_u32 v163, v160, 2, v163
	v_lshl_add_u32 v163, v162, 1, v163
	v_mul_u32_u24_e32 v163, 0x800, v163
	v_add_u32_e32 v240, v163, v161
	v_add_u32_e32 v241, 0xfc00, v240
	v_subrev_u32_e32 v242, 0xfc00, v241
	v_add_u32_e32 v243, 0xfc00, v242
	v_and_b32_e32 v160, 15, v192
	v_bfe_u32 v161, v192, 4, 2
	v_and_b32_e32 v162, 7, v160
	v_xor_b32_e32 v161, v161, v162
	v_lshlrev_b32_e32 v161, 4, v161
	v_lshl_add_u32 v161, v160, 7, v161
	v_lshrrev_b32_e32 v162, 7, v192
	v_lshl_add_u32 v244, v162, 13, v161
	v_bfe_u32 v162, v192, 6, 1
	v_lshl_add_u32 v246, v162, 13, v161
	v_add_u32_e32 v246, 0x4000, v246
	v_xor_b32_e32 v245, 64, v244
	v_xor_b32_e32 v247, 64, v246
	v_lshrrev_b32_e32 v160, 6, v192
	s_nop 0
	v_readfirstlane_b32 s94, v160
	v_readfirstlane_b32 s90, v248
	v_readfirstlane_b32 s91, v249
	v_readfirstlane_b32 s92, v250
	v_readfirstlane_b32 s93, v251
	s_mul_i32 s95, s94, 0x4000
	s_sub_u32 s90, s90, s95
	s_subb_u32 s91, s91, 0
	s_mul_i32 s95, s94, 0x4000
	s_sub_u32 s92, s92, s95
	s_subb_u32 s93, s93, 0
	s_lshl_b32 s94, s94, 10
	s_waitcnt lgkmcnt(0)
	s_barrier
	s_lshl_b32 s95, s94, 2
	s_add_u32 m0, s95, 0x0
	s_nop 0
	global_load_lds_dwordx4 v236, s[90:91]
	global_load_lds_dwordx4 v237, s[90:91] offset:1024
	global_load_lds_dwordx4 v238, s[90:91] offset:2048
	global_load_lds_dwordx4 v239, s[90:91] offset:3072
	s_mul_i32 s95, s94, 4
	s_add_u32 m0, s95, 0x4000
	s_nop 0
	global_load_lds_dwordx4 v240, s[92:93]
	global_load_lds_dwordx4 v241, s[92:93] offset:1024
	global_load_lds_dwordx4 v242, s[92:93] offset:2048
	global_load_lds_dwordx4 v243, s[92:93] offset:3072
	s_add_u32 s90, s90, 0x80
	s_addc_u32 s91, s91, 0
	s_add_u32 s92, s92, 0x80
	s_addc_u32 s93, s93, 0
	s_waitcnt vmcnt(0)
	s_barrier
	s_lshl_b32 s95, s94, 2
	s_add_u32 m0, s95, 0x8000
	s_nop 0
	global_load_lds_dwordx4 v236, s[90:91]
	global_load_lds_dwordx4 v237, s[90:91] offset:1024
	global_load_lds_dwordx4 v238, s[90:91] offset:2048
	global_load_lds_dwordx4 v239, s[90:91] offset:3072
	s_mul_i32 s95, s94, 4
	s_add_u32 m0, s95, 0xc000
	s_nop 0
	global_load_lds_dwordx4 v240, s[92:93]
	global_load_lds_dwordx4 v241, s[92:93] offset:1024
	global_load_lds_dwordx4 v242, s[92:93] offset:2048
	global_load_lds_dwordx4 v243, s[92:93] offset:3072
	s_add_u32 s90, s90, 0x80
	s_addc_u32 s91, s91, 0
	s_add_u32 s92, s92, 0x80
	s_addc_u32 s93, s93, 0
	ds_read_b128 v[110:113], v244 offset:0
	ds_read_b128 v[114:117], v244 offset:2048
	ds_read_b128 v[118:121], v244 offset:4096
	ds_read_b128 v[122:125], v244 offset:6144
	ds_read_b128 v[126:129], v246 offset:0
	ds_read_b128 v[130:133], v246 offset:2048
	ds_read_b128 v[134:137], v246 offset:4096
	ds_read_b128 v[138:141], v246 offset:6144
	s_movk_i32 s95, 0x6
	s_cmp_eq_u32 s95, 0
	s_cbranch_scc1 .Lgemm_x178
